# S5 pass 2: 12 tasks per workgroup (waves 0-3 two, waves 4-7 one) instead of 16 on half the workgroups and 8 on the rest
# speedup vs baseline: 1.0290x; 1.0133x over previous
.LBB0_177:
	v_readlane_b32 s4, v255, 29
	s_mul_i32 s6, s4, 12
	v_readlane_b32 s4, v253, 8
	s_add_i32 s4, s6, s4
	s_cmpk_gt_i32 s4, 0xbff
	s_cbranch_scc1 .LBB0_188
	v_ashrrev_i32_e32 v4, 5, v168
	v_lshlrev_b32_e32 v108, 3, v4
	v_readlane_b32 s8, v253, 4
	v_and_b32_e32 v167, 31, v168
	v_ashrrev_i32_e32 v109, 31, v108
	v_readlane_b32 s9, v253, 5
	v_lshlrev_b32_e32 v160, 5, v167
	v_and_b32_e32 v169, 15, v168
	s_waitcnt lgkmcnt(0)
	v_lshl_add_u64 v[0:1], v[108:109], 1, s[8:9]
	v_readlane_b32 s8, v253, 2
	v_ashrrev_i32_e32 v5, 4, v168
	v_lshl_add_u64 v[110:111], v[0:1], 0, v[160:161]
	v_lshlrev_b32_e32 v160, 8, v169
	v_readlane_b32 s9, v253, 3
	v_lshlrev_b32_e32 v2, 3, v5
	v_ashrrev_i32_e32 v3, 31, v2
	v_lshl_add_u64 v[0:1], s[8:9], 0, v[160:161]
	s_mul_i32 s8, s18, 0x300
	s_ashr_i32 s9, s8, 31
	s_mov_b32 s10, s18
	s_mov_b32 s7, s27
	v_readlane_b32 s12, v252, 3
	v_lshl_add_u64 v[112:113], v[2:3], 1, v[0:1]
	s_lshl_b64 s[8:9], s[8:9], 2
	v_readlane_b32 s22, v252, 13
	v_xor_b32_e32 v0, 32, v220
	v_readlane_b32 s23, v252, 14
	v_readlane_b32 s27, v252, 18
	s_add_u32 s8, s22, s8
	v_lshlrev_b32_e32 v114, 2, v5
	v_cmp_lt_i32_e32 vcc, v0, v221
	s_mov_b32 s27, s7
	s_addc_u32 s9, s23, s9
	v_ashrrev_i32_e32 v115, 31, v114
	v_cndmask_b32_e32 v0, v220, v0, vcc
	v_lshlrev_b32_e32 v160, 2, v167
	v_readlane_b32 s7, v253, 10
	v_and_b32_e32 v1, -16, v168
	v_lshl_add_u64 v[116:117], v[114:115], 2, s[8:9]
	v_lshlrev_b32_e32 v234, 2, v0
	v_add_u32_e32 v0, s7, v160
	v_add_u32_e32 v1, s7, v1
	v_readlane_b32 s8, v252, 40
	s_movk_i32 s7, 0x440
	v_readlane_b32 s9, v252, 41
	v_mul_lo_u32 v2, v4, s7
	v_readlane_b32 s7, v253, 8
	v_readlane_b32 s20, v252, 11
	v_readlane_b32 s21, v252, 12
	v_lshl_add_u64 v[118:119], v[114:115], 1, s[8:9]
	s_add_i32 s8, s6, s7
	v_readlane_b32 s6, v254, 39
	v_readlane_b32 s18, v252, 9
	v_readlane_b32 s20, v255, 17
	v_mul_u32_u24_e32 v3, 0x110, v169
	v_readlane_b32 s7, v254, 40
	s_mov_b32 s18, s10
	v_readlane_b32 s21, v255, 18
	v_cmp_gt_u32_e64 s[36:37], 32, v168
	v_lshl_add_u64 v[120:121], s[6:7], 0, v[160:161]
	v_add_u32_e32 v235, v0, v2
	v_add_u32_e32 v236, v1, v3
	v_readlane_b32 s13, v252, 4
	v_readlane_b32 s14, v252, 5
	v_readlane_b32 s15, v252, 6
	v_readlane_b32 s16, v252, 7
	v_readlane_b32 s17, v252, 8
	v_readlane_b32 s19, v252, 10
	v_readlane_b32 s24, v252, 15
	v_readlane_b32 s25, v252, 16
	v_readlane_b32 s26, v252, 17

.LBB0_185:
	v_or_b32_e32 v204, s11, v239
	v_cndmask_b32_e64 v0, 0, 1, s[6:7]
	v_ashrrev_i32_e32 v205, 31, v204
	v_cmp_ne_u32_e32 vcc, 1, v0
	v_lshlrev_b64 v[0:1], 11, v[204:205]
	v_or_b32_e32 v200, 16, v204
	v_lshl_add_u64 v[0:1], v[146:147], 0, v[0:1]
	v_ashrrev_i32_e32 v201, 31, v200
	global_load_dwordx2 v[206:207], v[0:1], off
	v_lshlrev_b64 v[0:1], 11, v[200:201]
	v_lshl_add_u64 v[0:1], v[146:147], 0, v[0:1]
	global_load_dwordx2 v[202:203], v[0:1], off
	s_waitcnt vmcnt(2)
	v_cndmask_b32_e64 v3, v107, v103, s[6:7]
	v_cndmask_b32_e64 v2, v106, v102, s[6:7]
	v_cndmask_b32_e64 v1, v105, v101, s[6:7]
	v_cndmask_b32_e64 v0, v104, v100, s[6:7]
	s_mov_b32 s11, 32
	s_and_b64 vcc, exec, vcc
	v_mfma_f32_32x32x16_bf16 v[32:47], v[0:3], v[72:75], 0
	v_mfma_f32_32x32x16_bf16 v[48:63], v[0:3], v[64:67], 0
	s_nop 10
	v_mul_f32_e64 v162, v190, v32
	v_mul_f32_e64 v163, v191, v32
	v_mov_b32_e32 v223, v34
	v_mfma_f32_32x32x16_bf16 v[16:31], v[0:3], v[68:71], 0
	v_fma_f32 v164, v126, v48, -v162
	v_fma_f32 v165, v127, v49, -v163
	v_fma_f32 v162, v126, v48, v162
	v_fma_f32 v163, v127, v48, v163
	v_mov_b32_e32 v222, v50
	v_mov_b32_e32 v165, v163
	v_mov_b32_e32 v162, v49
	v_mov_b32_e32 v163, v33
	v_pk_add_f32 v[162:163], v[162:163], v[164:165]
	v_mov_b32_e32 v34, v51
	v_mul_f32_e32 v208, v128, v162
	v_pk_fma_f32 v[210:211], v[128:129], v[162:163], v[208:209] op_sel_hi:[1,1,0]
	v_pk_mul_f32 v[208:209], v[190:191], v[36:37] op_sel_hi:[1,0]
	v_mul_f32_e32 v164, v127, v163
	v_pk_fma_f32 v[212:213], v[126:127], v[52:53], v[208:209] neg_lo:[0,0,1] neg_hi:[0,0,1]
	v_pk_fma_f32 v[208:209], v[126:127], v[52:53], v[208:209] op_sel_hi:[1,0,1]
	v_pk_fma_f32 v[164:165], v[126:127], v[162:163], v[164:165] op_sel_hi:[1,1,0] neg_lo:[0,0,1] neg_hi:[0,0,1]
	v_mov_b32_e32 v213, v209
	v_mov_b32_e32 v208, v53
	v_mov_b32_e32 v209, v37
	v_pk_add_f32 v[208:209], v[208:209], v[212:213]
	v_mov_b32_e32 v165, v211
	v_mul_f32_e32 v210, v127, v209
	v_pk_fma_f32 v[212:213], v[126:127], v[208:209], v[210:211] op_sel_hi:[1,1,0] neg_lo:[0,0,1] neg_hi:[0,0,1]
	v_mul_f32_e32 v210, v128, v208
	v_pk_add_f32 v[164:165], v[222:223], v[164:165]
	v_pk_fma_f32 v[214:215], v[128:129], v[208:209], v[210:211] op_sel_hi:[1,1,0]
	v_pk_mul_f32 v[210:211], v[158:159], v[164:165]
	v_mov_b32_e32 v49, v32
	v_pk_fma_f32 v[222:223], v[156:157], v[164:165], v[210:211] op_sel:[0,0,1] op_sel_hi:[1,1,0] neg_lo:[0,0,1] neg_hi:[0,0,1]
	v_pk_fma_f32 v[210:211], v[156:157], v[164:165], v[210:211] op_sel:[0,0,1] op_sel_hi:[1,1,0]
	v_mov_b32_e32 v213, v215
	v_mov_b32_e32 v223, v211
	v_pk_add_f32 v[34:35], v[34:35], v[222:223]
	ds_bpermute_b32 v37, v234, v34
	ds_bpermute_b32 v53, v234, v35
	v_pk_mul_f32 v[210:211], v[154:155], v[196:197] op_sel_hi:[1,0]
	v_mfma_f32_32x32x16_bf16 v[0:15], v[0:3], v[76:79], 0
	v_fma_f32 v222, v150, v198, -v210
	v_fma_f32 v223, v151, v199, -v211
	v_fma_f32 v210, v150, v198, v210
	v_fma_f32 v211, v151, v198, v211
	s_waitcnt lgkmcnt(0)
	v_cndmask_b32_e64 v51, v53, v35, s[36:37]
	v_cndmask_b32_e64 v50, v37, v34, s[36:37]
	v_mov_b32_e32 v223, v211
	v_pk_add_f32 v[50:51], v[222:223], v[50:51]
	s_nop 0
	v_cndmask_b32_e64 v199, v51, v196, s[36:37]
	v_cndmask_b32_e64 v198, v50, v198, s[36:37]
	v_pk_fma_f32 v[32:33], v[156:157], v[198:199], v[48:49]
	v_pk_mul_f32 v[48:49], v[158:159], v[198:199]
	s_nop 0
	v_pk_add_f32 v[210:211], v[32:33], v[48:49] op_sel:[0,1] op_sel_hi:[1,0] neg_lo:[0,1] neg_hi:[0,1]
	v_pk_add_f32 v[32:33], v[32:33], v[48:49] op_sel:[0,1] op_sel_hi:[1,0]
	v_pk_mul_f32 v[48:49], v[172:173], v[198:199]
	v_cvt_pk_bf16_f32 v245, v210, v33
	v_pk_fma_f32 v[32:33], v[170:171], v[198:199], v[162:163]
	s_nop 0
	v_pk_add_f32 v[162:163], v[32:33], v[48:49] op_sel:[0,1] op_sel_hi:[1,0] neg_lo:[0,1] neg_hi:[0,1]
	v_pk_add_f32 v[32:33], v[32:33], v[48:49] op_sel:[0,1] op_sel_hi:[1,0]
	v_pk_mul_f32 v[48:49], v[138:139], v[198:199]
	v_cvt_pk_bf16_f32 v244, v162, v33
	v_pk_fma_f32 v[32:33], v[136:137], v[198:199], v[164:165]
	s_nop 0
	v_pk_add_f32 v[162:163], v[32:33], v[48:49] op_sel:[0,1] op_sel_hi:[1,0] neg_lo:[0,1] neg_hi:[0,1]
	v_pk_add_f32 v[32:33], v[32:33], v[48:49] op_sel:[0,1] op_sel_hi:[1,0]
	v_pk_mul_f32 v[48:49], v[176:177], v[198:199]
	v_cvt_pk_bf16_f32 v243, v162, v33
	v_pk_fma_f32 v[32:33], v[174:175], v[198:199], v[34:35]
	v_cndmask_b32_e64 v35, v35, v53, s[36:37]
	v_pk_add_f32 v[162:163], v[32:33], v[48:49] op_sel:[0,1] op_sel_hi:[1,0] neg_lo:[0,1] neg_hi:[0,1]
	v_pk_add_f32 v[32:33], v[32:33], v[48:49] op_sel:[0,1] op_sel_hi:[1,0]
	v_cndmask_b32_e64 v34, v34, v37, s[36:37]
	v_cvt_pk_bf16_f32 v242, v162, v33
	v_mov_b32_e32 v32, v54
	v_mov_b32_e32 v33, v38
	v_pk_add_f32 v[32:33], v[32:33], v[212:213]
	v_mov_b32_e32 v38, v55
	v_pk_mul_f32 v[48:49], v[158:159], v[32:33]
	v_mov_b32_e32 v53, v36
	v_pk_fma_f32 v[162:163], v[156:157], v[32:33], v[48:49] op_sel:[0,0,1] op_sel_hi:[1,1,0] neg_lo:[0,0,1] neg_hi:[0,0,1]
	v_pk_fma_f32 v[48:49], v[156:157], v[32:33], v[48:49] op_sel:[0,0,1] op_sel_hi:[1,1,0]
	s_nop 0
	v_mov_b32_e32 v163, v49
	v_pk_add_f32 v[198:199], v[38:39], v[162:163]
	v_pk_mul_f32 v[48:49], v[176:177], v[50:51]
	ds_bpermute_b32 v246, v234, v198
	ds_bpermute_b32 v247, v234, v199
	v_pk_fma_f32 v[54:55], v[174:175], v[50:51], v[48:49] op_sel:[0,0,1] op_sel_hi:[1,1,0] neg_lo:[0,0,1] neg_hi:[0,0,1]
	v_pk_fma_f32 v[48:49], v[174:175], v[50:51], v[48:49] op_sel:[0,0,1] op_sel_hi:[1,1,0]
	s_waitcnt lgkmcnt(1)
	v_cndmask_b32_e64 v38, v246, v198, s[36:37]
	v_mov_b32_e32 v55, v49
	v_pk_add_f32 v[34:35], v[34:35], v[54:55]
	s_waitcnt lgkmcnt(0)
	v_cndmask_b32_e64 v39, v247, v199, s[36:37]
	v_pk_mul_f32 v[48:49], v[176:177], v[34:35]
	s_nop 0
	v_pk_fma_f32 v[50:51], v[174:175], v[34:35], v[48:49] op_sel:[0,0,1] op_sel_hi:[1,1,0] neg_lo:[0,0,1] neg_hi:[0,0,1]
	v_pk_fma_f32 v[48:49], v[174:175], v[34:35], v[48:49] op_sel:[0,0,1] op_sel_hi:[1,1,0]
	s_nop 0
	v_mov_b32_e32 v51, v49
	v_pk_add_f32 v[214:215], v[38:39], v[50:51]
	s_nop 0
	v_cndmask_b32_e64 v35, v215, v35, s[36:37]
	v_cndmask_b32_e64 v34, v214, v34, s[36:37]
	v_pk_fma_f32 v[36:37], v[156:157], v[34:35], v[52:53]
	v_pk_mul_f32 v[38:39], v[158:159], v[34:35]
	v_pk_fma_f32 v[32:33], v[136:137], v[34:35], v[32:33]
	v_pk_add_f32 v[48:49], v[36:37], v[38:39] op_sel:[0,1] op_sel_hi:[1,0] neg_lo:[0,1] neg_hi:[0,1]
	v_pk_add_f32 v[36:37], v[36:37], v[38:39] op_sel:[0,1] op_sel_hi:[1,0]
	v_pk_mul_f32 v[38:39], v[172:173], v[34:35]
	v_cvt_pk_bf16_f32 v241, v48, v37
	v_pk_fma_f32 v[36:37], v[170:171], v[34:35], v[208:209]
	v_pk_mul_f32 v[224:225], v[176:177], v[214:215]
	v_pk_add_f32 v[48:49], v[36:37], v[38:39] op_sel:[0,1] op_sel_hi:[1,0] neg_lo:[0,1] neg_hi:[0,1]
	v_pk_add_f32 v[36:37], v[36:37], v[38:39] op_sel:[0,1] op_sel_hi:[1,0]
	v_pk_fma_f32 v[226:227], v[174:175], v[214:215], v[224:225] op_sel:[0,0,1] op_sel_hi:[1,1,0] neg_lo:[0,0,1] neg_hi:[0,0,1]
	v_cvt_pk_bf16_f32 v240, v48, v37
	v_pk_mul_f32 v[36:37], v[138:139], v[34:35]
	v_pk_fma_f32 v[214:215], v[174:175], v[214:215], v[224:225] op_sel:[0,0,1] op_sel_hi:[1,1,0]
	v_pk_add_f32 v[38:39], v[32:33], v[36:37] op_sel:[0,1] op_sel_hi:[1,0] neg_lo:[0,1] neg_hi:[0,1]
	v_pk_add_f32 v[32:33], v[32:33], v[36:37] op_sel:[0,1] op_sel_hi:[1,0]
	v_mov_b32_e32 v227, v215
	v_cvt_pk_bf16_f32 v205, v38, v33
	v_pk_fma_f32 v[32:33], v[174:175], v[34:35], v[198:199]
	v_pk_mul_f32 v[34:35], v[176:177], v[34:35]
	v_cndmask_b32_e64 v199, v199, v247, s[36:37]
	v_pk_add_f32 v[36:37], v[32:33], v[34:35] op_sel:[0,1] op_sel_hi:[1,0] neg_lo:[0,1] neg_hi:[0,1]
	v_pk_add_f32 v[32:33], v[32:33], v[34:35] op_sel:[0,1] op_sel_hi:[1,0]
	v_cndmask_b32_e64 v198, v198, v246, s[36:37]
	v_cvt_pk_bf16_f32 v201, v36, v33
	v_pk_mul_f32 v[32:33], v[192:193], v[0:1] op_sel_hi:[1,0]
	v_pk_add_f32 v[198:199], v[198:199], v[226:227]
	v_pk_fma_f32 v[34:35], v[130:131], v[16:17], v[32:33]
	v_pk_fma_f32 v[32:33], v[130:131], v[16:17], v[32:33] op_sel_hi:[1,0,1] neg_lo:[0,0,1] neg_hi:[0,0,1]
	v_mov_b32_e32 v164, v199
	v_mov_b32_e32 v35, v33
	v_mov_b32_e32 v32, v1
	v_mov_b32_e32 v33, v17
	v_pk_add_f32 v[208:209], v[32:33], v[34:35]
	v_mov_b32_e32 v162, v198
	v_pk_mul_f32 v[32:33], v[182:183], v[208:209]
	s_nop 0
	v_pk_fma_f32 v[34:35], v[184:185], v[208:209], v[32:33] op_sel:[0,0,1] op_sel_hi:[1,1,0] neg_lo:[1,0,0] neg_hi:[1,0,0]
	v_pk_fma_f32 v[32:33], v[184:185], v[208:209], v[32:33] op_sel:[0,0,1] op_sel_hi:[1,1,0]
	s_nop 0
	v_mov_b32_e32 v35, v33
	v_mov_b32_e32 v32, v18
	v_mov_b32_e32 v33, v2
	v_pk_add_f32 v[210:211], v[32:33], v[34:35]
	v_mov_b32_e32 v2, v19
	v_pk_mul_f32 v[32:33], v[184:185], v[210:211]
	s_nop 0
	v_pk_fma_f32 v[34:35], v[182:183], v[210:211], v[32:33] op_sel:[0,0,1] op_sel_hi:[1,1,0] neg_lo:[0,0,1] neg_hi:[0,0,1]
	v_pk_fma_f32 v[32:33], v[182:183], v[210:211], v[32:33] op_sel:[0,0,1] op_sel_hi:[1,1,0]
	s_nop 0
	v_mov_b32_e32 v35, v33
	v_pk_add_f32 v[212:213], v[2:3], v[34:35]
	ds_bpermute_b32 v1, v234, v212
	ds_bpermute_b32 v2, v234, v213
	v_pk_mul_f32 v[32:33], v[186:187], v[196:197] op_sel:[0,1]
	s_waitcnt lgkmcnt(1)
	v_cndmask_b32_e64 v18, v1, v212, s[36:37]
	v_pk_fma_f32 v[34:35], v[152:153], v[160:161], v[32:33] neg_lo:[0,0,1] neg_hi:[0,0,1]
	v_pk_fma_f32 v[32:33], v[152:153], v[160:161], v[32:33] op_sel_hi:[1,0,1]
	s_waitcnt lgkmcnt(0)
	v_cndmask_b32_e64 v19, v2, v213, s[36:37]
	v_mov_b32_e32 v35, v33
	v_pk_add_f32 v[18:19], v[34:35], v[18:19]
	v_cndmask_b32_e64 v3, v213, v2, s[36:37]
	v_pk_mul_f32 v[32:33], v[188:189], v[18:19]
	v_cndmask_b32_e64 v248, v18, v160, s[36:37]
	v_cndmask_b32_e64 v249, v19, v197, s[36:37]
	v_pk_fma_f32 v[34:35], v[180:181], v[18:19], v[32:33] op_sel:[0,0,1] op_sel_hi:[1,1,0] neg_lo:[0,0,1] neg_hi:[0,0,1]
	v_pk_fma_f32 v[18:19], v[180:181], v[18:19], v[32:33] op_sel:[0,0,1] op_sel_hi:[1,1,0]
	v_cndmask_b32_e64 v2, v212, v1, s[36:37]
	v_mov_b32_e32 v35, v19
	v_pk_mul_f32 v[18:19], v[194:195], v[4:5] op_sel_hi:[1,0]
	v_pk_add_f32 v[2:3], v[2:3], v[34:35]
	v_pk_fma_f32 v[32:33], v[178:179], v[20:21], v[18:19] neg_lo:[0,0,1] neg_hi:[0,0,1]
	v_pk_fma_f32 v[18:19], v[178:179], v[20:21], v[18:19] op_sel_hi:[1,0,1]
	v_fma_f32 v16, v123, v248, v16
	v_mov_b32_e32 v33, v19
	v_mov_b32_e32 v18, v21
	v_mov_b32_e32 v19, v5
	v_pk_add_f32 v[50:51], v[18:19], v[32:33]
	v_fma_f32 v0, v123, v249, v0
	v_pk_mul_f32 v[18:19], v[184:185], v[50:51]
	v_fma_f32 v16, -v125, v249, v16
	v_pk_fma_f32 v[32:33], v[182:183], v[50:51], v[18:19] op_sel:[0,0,1] op_sel_hi:[1,1,0] neg_lo:[0,0,1] neg_hi:[0,0,1]
	v_pk_fma_f32 v[18:19], v[182:183], v[50:51], v[18:19] op_sel:[0,0,1] op_sel_hi:[1,1,0]
	v_fmac_f32_e32 v0, v125, v248
	v_mov_b32_e32 v33, v19
	v_mov_b32_e32 v18, v22
	v_mov_b32_e32 v19, v6
	v_pk_add_f32 v[52:53], v[18:19], v[32:33]
	v_mov_b32_e32 v6, v23
	v_pk_mul_f32 v[18:19], v[184:185], v[52:53]
	v_cvt_pk_bf16_f32 v0, v16, v0
	v_pk_fma_f32 v[32:33], v[182:183], v[52:53], v[18:19] op_sel:[0,0,1] op_sel_hi:[1,1,0] neg_lo:[0,0,1] neg_hi:[0,0,1]
	v_pk_fma_f32 v[18:19], v[182:183], v[52:53], v[18:19] op_sel:[0,0,1] op_sel_hi:[1,1,0]
	ds_write2_b32 v235, v245, v0 offset1:32
	v_mov_b32_e32 v33, v19
	v_pk_add_f32 v[54:55], v[6:7], v[32:33]
	ds_bpermute_b32 v1, v234, v54
	ds_bpermute_b32 v5, v234, v55
	v_pk_mul_f32 v[18:19], v[188:189], v[2:3]
	v_fma_f32 v0, v133, v248, v209
	v_pk_fma_f32 v[22:23], v[180:181], v[2:3], v[18:19] op_sel:[0,0,1] op_sel_hi:[1,1,0] neg_lo:[0,0,1] neg_hi:[0,0,1]
	v_pk_fma_f32 v[18:19], v[180:181], v[2:3], v[18:19] op_sel:[0,0,1] op_sel_hi:[1,1,0]
	s_waitcnt lgkmcnt(0)
	v_cndmask_b32_e64 v7, v5, v55, s[36:37]
	v_cndmask_b32_e64 v6, v1, v54, s[36:37]
	v_mov_b32_e32 v23, v19
	v_pk_add_f32 v[6:7], v[6:7], v[22:23]
	v_cndmask_b32_e64 v1, v54, v1, s[36:37]
	v_cndmask_b32_e64 v17, v6, v2, s[36:37]
	v_cndmask_b32_e64 v21, v7, v3, s[36:37]
	v_pk_mul_f32 v[2:3], v[152:153], v[6:7]
	v_mov_b32_e32 v22, v57
	v_sub_f32_e32 v2, v2, v3
	v_add_f32_e32 v163, v1, v2
	v_pk_mul_f32 v[2:3], v[186:187], v[6:7]
	v_mov_b32_e32 v6, v40
	v_mov_b32_e32 v7, v8
	v_add_f32_e32 v1, v2, v3
	v_mov_b32_e32 v2, v56
	v_mov_b32_e32 v3, v24
	v_pk_mul_f32 v[18:19], v[124:125], v[6:7]
	v_pk_mul_f32 v[6:7], v[122:123], v[6:7]
	v_pk_fma_f32 v[18:19], v[122:123], v[2:3], v[18:19] neg_lo:[0,0,1] neg_hi:[0,0,1]
	v_pk_fma_f32 v[2:3], v[124:125], v[2:3], v[6:7]
	v_mov_b32_e32 v6, v41
	v_mov_b32_e32 v7, v9
	v_mov_b32_e32 v23, v25
	v_pk_add_f32 v[34:35], v[6:7], v[2:3]
	v_pk_add_f32 v[32:33], v[22:23], v[18:19]
	v_pk_mul_f32 v[2:3], v[124:125], v[34:35]
	v_mov_b32_e32 v6, v58
	v_pk_fma_f32 v[2:3], v[122:123], v[32:33], v[2:3] neg_lo:[0,0,1] neg_hi:[0,0,1]
	v_mov_b32_e32 v7, v26
	v_pk_add_f32 v[36:37], v[6:7], v[2:3]
	v_pk_mul_f32 v[2:3], v[124:125], v[32:33]
	v_mov_b32_e32 v6, v42
	v_pk_fma_f32 v[2:3], v[122:123], v[34:35], v[2:3]
	v_mov_b32_e32 v7, v10
	v_pk_add_f32 v[38:39], v[6:7], v[2:3]
	v_mov_b32_e32 v26, v59
	v_pk_mul_f32 v[2:3], v[124:125], v[38:39]
	v_mov_b32_e32 v10, v43
	v_pk_fma_f32 v[2:3], v[122:123], v[36:37], v[2:3] neg_lo:[0,0,1] neg_hi:[0,0,1]
	v_mov_b32_e32 v6, v44
	v_pk_add_f32 v[48:49], v[26:27], v[2:3]
	v_pk_mul_f32 v[2:3], v[124:125], v[36:37]
	v_mov_b32_e32 v7, v12
	v_pk_fma_f32 v[2:3], v[122:123], v[38:39], v[2:3]
	v_cndmask_b32_e64 v5, v55, v5, s[36:37]
	v_pk_add_f32 v[42:43], v[10:11], v[2:3]
	v_mov_b32_e32 v2, v60
	v_mov_b32_e32 v3, v28
	v_pk_mul_f32 v[10:11], v[124:125], v[6:7]
	v_pk_mul_f32 v[6:7], v[122:123], v[6:7]
	v_pk_fma_f32 v[10:11], v[122:123], v[2:3], v[10:11] neg_lo:[0,0,1] neg_hi:[0,0,1]
	v_mov_b32_e32 v18, v61
	v_mov_b32_e32 v19, v29
	v_pk_fma_f32 v[2:3], v[124:125], v[2:3], v[6:7]
	v_mov_b32_e32 v6, v45
	v_mov_b32_e32 v7, v13
	v_add_f32_e32 v165, v5, v1
	ds_bpermute_b32 v1, v234, v48
	ds_bpermute_b32 v9, v234, v49
	v_pk_add_f32 v[10:11], v[18:19], v[10:11]
	v_pk_add_f32 v[18:19], v[6:7], v[2:3]
	ds_bpermute_b32 v5, v234, v42
	ds_bpermute_b32 v25, v234, v43
	v_pk_mul_f32 v[2:3], v[124:125], v[18:19]
	v_mov_b32_e32 v6, v62
	v_pk_fma_f32 v[2:3], v[122:123], v[10:11], v[2:3] neg_lo:[0,0,1] neg_hi:[0,0,1]
	v_mov_b32_e32 v7, v30
	v_pk_add_f32 v[22:23], v[6:7], v[2:3]
	v_pk_mul_f32 v[2:3], v[124:125], v[10:11]
	v_mov_b32_e32 v6, v46
	v_pk_fma_f32 v[2:3], v[122:123], v[18:19], v[2:3]
	v_mov_b32_e32 v7, v14
	v_pk_mul_f32 v[214:215], v[142:143], v[164:165]
	s_waitcnt lgkmcnt(2)
	v_cndmask_b32_e64 v59, v9, v49, s[36:37]
	v_cndmask_b32_e64 v58, v1, v48, s[36:37]
	v_pk_add_f32 v[26:27], v[6:7], v[2:3]
	v_pk_mul_f32 v[224:225], v[142:143], v[162:163]
	v_pk_fma_f32 v[214:215], v[140:141], v[162:163], v[214:215] neg_lo:[0,0,1] neg_hi:[0,0,1]
	s_waitcnt lgkmcnt(0)
	v_cndmask_b32_e64 v197, v25, v43, s[36:37]
	v_cndmask_b32_e64 v196, v5, v42, s[36:37]
	v_pk_mul_f32 v[2:3], v[124:125], v[26:27]
	v_pk_add_f32 v[58:59], v[58:59], v[214:215]
	v_pk_fma_f32 v[214:215], v[140:141], v[164:165], v[224:225]
	v_fmac_f32_e32 v208, v133, v249
	v_pk_fma_f32 v[2:3], v[122:123], v[22:23], v[2:3] neg_lo:[0,0,1] neg_hi:[0,0,1]
	v_mov_b32_e32 v30, v63
	v_pk_mul_f32 v[6:7], v[124:125], v[22:23]
	v_pk_add_f32 v[196:197], v[196:197], v[214:215]
	v_fma_f32 v0, -v135, v249, v0
	v_fmac_f32_e32 v208, v135, v248
	v_pk_add_f32 v[2:3], v[30:31], v[2:3]
	v_pk_fma_f32 v[6:7], v[122:123], v[26:27], v[6:7]
	v_mov_b32_e32 v14, v47
	v_cndmask_b32_e64 v215, v196, v199, s[36:37]
	v_cndmask_b32_e64 v214, v58, v198, s[36:37]
	v_pk_mul_f32 v[198:199], v[142:143], v[196:197]
	v_cvt_pk_bf16_f32 v0, v0, v208
	ds_bpermute_b32 v13, v234, v2
	v_pk_add_f32 v[6:7], v[14:15], v[6:7]
	ds_bpermute_b32 v45, v234, v3
	v_cndmask_b32_e64 v15, v49, v9, s[36:37]
	v_cndmask_b32_e64 v14, v48, v1, s[36:37]
	v_pk_fma_f32 v[198:199], v[140:141], v[58:59], v[198:199] neg_lo:[0,0,1] neg_hi:[0,0,1]
	ds_write2_b32 v235, v244, v0 offset0:68 offset1:100
	v_fma_f32 v0, v237, v248, v210
	v_fmac_f32_e32 v211, v237, v249
	v_pk_add_f32 v[198:199], v[14:15], v[198:199]
	v_pk_mul_f32 v[14:15], v[140:141], v[196:197]
	v_fma_f32 v0, -v238, v249, v0
	v_fmac_f32_e32 v211, v238, v248
	ds_bpermute_b32 v29, v234, v6
	v_cndmask_b32_e64 v31, v43, v25, s[36:37]
	v_cndmask_b32_e64 v30, v42, v5, s[36:37]
	ds_bpermute_b32 v1, v234, v7
	v_pk_fma_f32 v[14:15], v[142:143], v[58:59], v[14:15]
	v_cvt_pk_bf16_f32 v0, v0, v211
	v_pk_add_f32 v[30:31], v[30:31], v[14:15]
	ds_write2_b32 v235, v243, v0 offset0:136 offset1:168
	v_fma_f32 v0, v141, v248, v212
	v_fmac_f32_e32 v213, v141, v249
	v_pk_mul_f32 v[14:15], v[142:143], v[30:31]
	v_fma_f32 v0, -v143, v249, v0
	v_fmac_f32_e32 v213, v143, v248
	s_waitcnt lgkmcnt(4)
	v_cndmask_b32_e64 v47, v45, v3, s[36:37]
	v_cndmask_b32_e64 v46, v13, v2, s[36:37]
	v_pk_fma_f32 v[14:15], v[140:141], v[198:199], v[14:15] neg_lo:[0,0,1] neg_hi:[0,0,1]
	v_cvt_pk_bf16_f32 v0, v0, v213
	v_pk_add_f32 v[46:47], v[46:47], v[14:15]
	v_pk_mul_f32 v[14:15], v[142:143], v[198:199]
	ds_write2_b32 v235, v242, v0 offset0:204 offset1:236
	v_fma_f32 v0, v123, v17, v20
	v_fma_f32 v4, v123, v21, v4
	s_waitcnt lgkmcnt(2)
	v_cndmask_b32_e64 v63, v1, v7, s[36:37]
	v_cndmask_b32_e64 v62, v29, v6, s[36:37]
	v_pk_fma_f32 v[14:15], v[140:141], v[30:31], v[14:15]
	v_fma_f32 v0, -v125, v21, v0
	v_fmac_f32_e32 v4, v125, v17
	v_pk_add_f32 v[62:63], v[62:63], v[14:15]
	v_cvt_pk_bf16_f32 v0, v0, v4
	v_add_u32_e32 v4, 0x800, v235
	v_mov_b32_e32 v14, v46
	v_mov_b32_e32 v15, v62
	ds_write2_b32 v4, v241, v0 offset0:32 offset1:64
	v_fma_f32 v0, v133, v17, v50
	v_fmac_f32_e32 v51, v133, v21
	v_cndmask_b32_e64 v223, v7, v1, s[36:37]
	v_cndmask_b32_e64 v1, v46, v198, s[36:37]
	v_cndmask_b32_e64 v30, v62, v30, s[36:37]
	v_pk_mul_f32 v[14:15], v[150:151], v[14:15]
	v_fma_f32 v0, -v135, v21, v0
	v_fmac_f32_e32 v51, v135, v17
	v_cndmask_b32_e64 v41, v2, v13, s[36:37]
	v_sub_f32_e32 v5, v14, v15
	v_fmac_f32_e32 v60, v122, v1
	v_fmac_f32_e32 v44, v122, v30
	v_cvt_pk_bf16_f32 v0, v0, v51
	v_add_f32_e32 v198, v41, v5
	v_fma_f32 v5, -v124, v30, v60
	v_fmac_f32_e32 v44, v124, v1
	ds_write2_b32 v4, v240, v0 offset0:100 offset1:132
	v_fma_f32 v0, v237, v17, v52
	v_fmac_f32_e32 v53, v237, v21
	v_cvt_pk_bf16_f32 v13, v5, v44
	v_fma_f32 v5, v132, v1, v10
	v_fma_f32 v9, v132, v30, v18
	v_fma_f32 v0, -v238, v21, v0
	v_fmac_f32_e32 v53, v238, v17
	v_fma_f32 v5, -v134, v30, v5
	v_fmac_f32_e32 v9, v134, v1
	v_cvt_pk_bf16_f32 v0, v0, v53
	v_pk_mul_f32 v[14:15], v[140:141], v[62:63]
	v_mov_b32_e32 v57, v40
	v_cvt_pk_bf16_f32 v9, v5, v9
	v_fma_f32 v5, v136, v1, v22
	v_fma_f32 v10, v136, v30, v26
	ds_write2_b32 v4, v205, v0 offset0:168 offset1:200
	v_fma_f32 v0, v141, v17, v54
	v_fmac_f32_e32 v55, v141, v21
	v_pk_fma_f32 v[224:225], v[142:143], v[46:47], v[14:15]
	v_pk_fma_f32 v[14:15], v[156:157], v[214:215], v[56:57]
	v_pk_mul_f32 v[40:41], v[158:159], v[214:215]
	v_fma_f32 v5, -v138, v30, v5
	v_fmac_f32_e32 v10, v138, v1
	v_fma_f32 v0, -v143, v21, v0
	v_fmac_f32_e32 v55, v143, v17
	v_pk_add_f32 v[56:57], v[14:15], v[40:41] op_sel:[0,1] op_sel_hi:[1,0] neg_lo:[0,1] neg_hi:[0,1]
	v_pk_add_f32 v[14:15], v[14:15], v[40:41] op_sel:[0,1] op_sel_hi:[1,0]
	v_mov_b32_e32 v40, v32
	v_mov_b32_e32 v41, v34
	v_cvt_pk_bf16_f32 v5, v5, v10
	v_cndmask_b32_e64 v10, v59, v163, s[36:37]
	v_cndmask_b32_e64 v18, v197, v165, s[36:37]
	v_cvt_pk_bf16_f32 v0, v0, v55
	v_add_u32_e32 v4, 0xa00, v235
	v_cvt_pk_bf16_f32 v15, v56, v15
	v_pk_fma_f32 v[40:41], v[170:171], v[214:215], v[40:41]
	v_pk_mul_f32 v[56:57], v[172:173], v[214:215]
	ds_write2_b32 v4, v201, v0 offset0:108 offset1:140
	v_fma_f32 v0, v123, v10, v24
	v_fma_f32 v4, v123, v18, v8
	v_pk_add_f32 v[226:227], v[40:41], v[56:57] op_sel:[0,1] op_sel_hi:[1,0] neg_lo:[0,1] neg_hi:[0,1]
	v_pk_add_f32 v[40:41], v[40:41], v[56:57] op_sel:[0,1] op_sel_hi:[1,0]
	v_fma_f32 v0, -v125, v18, v0
	v_fmac_f32_e32 v4, v125, v10
	v_cvt_pk_bf16_f32 v25, v226, v41
	v_mov_b32_e32 v40, v36
	v_mov_b32_e32 v41, v38
	v_cvt_pk_bf16_f32 v0, v0, v4
	v_add_u32_e32 v4, 0x1000, v235
	v_fmac_f32_e32 v33, v133, v10
	v_fmac_f32_e32 v35, v133, v18
	v_pk_fma_f32 v[40:41], v[136:137], v[214:215], v[40:41]
	v_pk_mul_f32 v[56:57], v[138:139], v[214:215]
	ds_write2_b32 v4, v15, v0 offset0:64 offset1:96
	v_fma_f32 v0, -v135, v18, v33
	v_fmac_f32_e32 v35, v135, v10
	v_pk_add_f32 v[226:227], v[40:41], v[56:57] op_sel:[0,1] op_sel_hi:[1,0] neg_lo:[0,1] neg_hi:[0,1]
	v_pk_add_f32 v[40:41], v[40:41], v[56:57] op_sel:[0,1] op_sel_hi:[1,0]
	v_cvt_pk_bf16_f32 v0, v0, v35
	v_fmac_f32_e32 v37, v237, v10
	v_fmac_f32_e32 v39, v237, v18
	v_cndmask_b32_e64 v222, v6, v29, s[36:37]
	v_cvt_pk_bf16_f32 v29, v226, v41
	v_mov_b32_e32 v40, v48
	v_mov_b32_e32 v41, v42
	v_fma_f32 v2, v140, v1, v2
	v_fma_f32 v6, v140, v30, v6
	ds_write2_b32 v4, v25, v0 offset0:132 offset1:164
	v_fma_f32 v0, -v238, v18, v37
	v_fmac_f32_e32 v39, v238, v10
	v_pk_fma_f32 v[40:41], v[174:175], v[214:215], v[40:41]
	v_pk_mul_f32 v[56:57], v[176:177], v[214:215]
	v_fma_f32 v2, -v142, v30, v2
	v_fmac_f32_e32 v6, v142, v1
	v_cvt_pk_bf16_f32 v0, v0, v39
	v_fmac_f32_e32 v49, v141, v10
	v_fmac_f32_e32 v43, v141, v18
	v_pk_add_f32 v[214:215], v[40:41], v[56:57] op_sel:[0,1] op_sel_hi:[1,0] neg_lo:[0,1] neg_hi:[0,1]
	v_pk_add_f32 v[40:41], v[40:41], v[56:57] op_sel:[0,1] op_sel_hi:[1,0]
	v_cvt_pk_bf16_f32 v1, v2, v6
	v_cndmask_b32_e64 v2, v47, v199, s[36:37]
	v_cndmask_b32_e64 v6, v63, v31, s[36:37]
	ds_write2_b32 v4, v29, v0 offset0:200 offset1:232
	v_fma_f32 v0, -v143, v18, v49
	v_fmac_f32_e32 v43, v143, v10
	v_cvt_pk_bf16_f32 v14, v214, v41
	v_cvt_pk_bf16_f32 v0, v0, v43
	v_add_u32_e32 v4, 0x1400, v235
	v_fmac_f32_e32 v28, v123, v2
	v_fmac_f32_e32 v12, v123, v6
	ds_write2_b32 v4, v14, v0 offset0:12 offset1:44
	v_fma_f32 v0, -v125, v6, v28
	v_fmac_f32_e32 v12, v125, v2
	v_cvt_pk_bf16_f32 v0, v0, v12
	v_add_u32_e32 v4, 0x1800, v235
	v_fmac_f32_e32 v11, v133, v2
	v_fmac_f32_e32 v19, v133, v6
	ds_write2_b32 v4, v13, v0 offset0:96 offset1:128
	v_fma_f32 v0, -v135, v6, v11
	v_fmac_f32_e32 v19, v135, v2
	v_cvt_pk_bf16_f32 v0, v0, v19
	v_fmac_f32_e32 v23, v237, v2
	v_fmac_f32_e32 v27, v237, v6
	ds_write2_b32 v4, v9, v0 offset0:164 offset1:196
	v_fma_f32 v0, -v238, v6, v23
	v_fmac_f32_e32 v27, v238, v2
	v_cndmask_b32_e64 v22, v3, v45, s[36:37]
	v_cvt_pk_bf16_f32 v0, v0, v27
	v_add_u32_e32 v4, 0x1a00, v235
	v_fmac_f32_e32 v3, v141, v2
	v_fmac_f32_e32 v7, v141, v6
	ds_write2_b32 v4, v5, v0 offset0:104 offset1:136
	v_fma_f32 v0, -v143, v6, v3
	v_fmac_f32_e32 v7, v143, v2
	v_cvt_pk_bf16_f32 v0, v0, v7
	v_add_u32_e32 v2, 0x1c00, v235
	ds_write2_b32 v2, v1, v0 offset0:44 offset1:76
	s_waitcnt lgkmcnt(0)
	ds_read_b128 v[0:3], v236
	ds_read_b128 v[4:7], v236 offset:64
	s_waitcnt lgkmcnt(1)
	v_mfma_f32_16x16x32_bf16 v[0:3], v[80:83], v[0:3], 0
	v_mov_b32_e32 v62, v47
	v_pk_mul_f32 v[30:31], v[152:153], v[62:63]
	v_pk_add_f32 v[196:197], v[222:223], v[224:225]
	s_waitcnt lgkmcnt(0)
	v_mfma_f32_16x16x32_bf16 v[0:3], v[84:87], v[4:7], v[0:3]
	ds_read_b128 v[4:7], v236 offset:128
	v_sub_f32_e32 v26, v30, v31
	v_add_f32_e32 v160, v22, v26
	s_waitcnt lgkmcnt(0)
	v_mfma_f32_16x16x32_bf16 v[0:3], v[88:91], v[4:7], v[0:3]
	ds_read_b128 v[4:7], v236 offset:192
	s_waitcnt lgkmcnt(0)
	v_mfma_f32_16x16x32_bf16 v[0:3], v[92:95], v[4:7], v[0:3]
	s_waitcnt vmcnt(1)
	v_lshlrev_b32_e32 v4, 16, v206
	v_and_b32_e32 v5, 0xffff0000, v206
	s_nop 4
	v_pk_fma_f32 v[0:1], v[96:97], v[4:5], v[0:1]
	s_nop 0
	v_mul_f32_e32 v4, 0x3d372713, v0
	v_mul_f32_e32 v5, 0x3d372713, v1
	v_mul_f32_e32 v4, v0, v4
	v_mul_f32_e32 v5, v1, v5
	v_fma_f32 v4, v0, v4, v0
	v_fma_f32 v5, v1, v5, v1
	v_mul_f32_e32 v4, 0xbfcc422a, v4
	v_mul_f32_e32 v5, 0xbfcc422a, v5
	v_mul_f32_e32 v4, 0x3fb8aa3b, v4
	v_mul_f32_e32 v5, 0x3fb8aa3b, v5
	v_exp_f32_e32 v4, v4
	v_exp_f32_e32 v5, v5
	v_add_f32_e32 v4, 1.0, v4
	v_add_f32_e32 v5, 1.0, v5
	v_rcp_f32_e32 v4, v4
	v_rcp_f32_e32 v5, v5
	s_nop 0
	v_pk_mul_f32 v[0:1], v[0:1], v[4:5]
	v_lshlrev_b32_e32 v4, 16, v207
	v_and_b32_e32 v5, 0xffff0000, v207
	v_pk_fma_f32 v[2:3], v[98:99], v[4:5], v[2:3]
	v_cvt_pk_bf16_f32 v0, v0, v1
	v_mul_f32_e32 v4, 0x3d372713, v2
	v_mul_f32_e32 v5, 0x3d372713, v3
	v_mul_f32_e32 v4, v2, v4
	v_mul_f32_e32 v5, v3, v5
	v_fma_f32 v4, v2, v4, v2
	v_fma_f32 v5, v3, v5, v3
	v_mul_f32_e32 v4, 0xbfcc422a, v4
	v_mul_f32_e32 v5, 0xbfcc422a, v5
	v_mul_f32_e32 v4, 0x3fb8aa3b, v4
	v_mul_f32_e32 v5, 0x3fb8aa3b, v5
	v_exp_f32_e32 v4, v4
	v_exp_f32_e32 v5, v5
	v_add_f32_e32 v4, 1.0, v4
	v_add_f32_e32 v5, 1.0, v5
	v_rcp_f32_e32 v4, v4
	v_rcp_f32_e32 v5, v5
	s_nop 0
	v_pk_mul_f32 v[2:3], v[2:3], v[4:5]
	s_nop 0
	v_cvt_pk_bf16_f32 v1, v2, v3
	v_mad_i64_i32 v[2:3], s[6:7], v204, s35, v[148:149]
	global_store_dwordx2 v[2:3], v[0:1], off
	ds_read_b128 v[0:3], v236 offset:4352
	ds_read_b128 v[4:7], v236 offset:4416
	s_waitcnt lgkmcnt(1)
	v_mfma_f32_16x16x32_bf16 v[0:3], v[80:83], v[0:3], 0
	s_waitcnt lgkmcnt(0)
	v_mfma_f32_16x16x32_bf16 v[0:3], v[84:87], v[4:7], v[0:3]
	ds_read_b128 v[4:7], v236 offset:4480
	s_waitcnt lgkmcnt(0)
	v_mfma_f32_16x16x32_bf16 v[0:3], v[88:91], v[4:7], v[0:3]
	ds_read_b128 v[4:7], v236 offset:4544
	s_waitcnt lgkmcnt(0)
	v_mfma_f32_16x16x32_bf16 v[0:3], v[92:95], v[4:7], v[0:3]
	s_waitcnt vmcnt(1)
	v_lshlrev_b32_e32 v4, 16, v202
	v_and_b32_e32 v5, 0xffff0000, v202
	s_nop 4
	v_pk_fma_f32 v[0:1], v[96:97], v[4:5], v[0:1]
	s_nop 0
	v_mul_f32_e32 v4, 0x3d372713, v0
	v_mul_f32_e32 v5, 0x3d372713, v1
	v_mul_f32_e32 v4, v0, v4
	v_mul_f32_e32 v5, v1, v5
	v_fma_f32 v4, v0, v4, v0
	v_fma_f32 v5, v1, v5, v1
	v_mul_f32_e32 v4, 0xbfcc422a, v4
	v_mul_f32_e32 v5, 0xbfcc422a, v5
	v_mul_f32_e32 v4, 0x3fb8aa3b, v4
	v_mul_f32_e32 v5, 0x3fb8aa3b, v5
	v_exp_f32_e32 v4, v4
	v_exp_f32_e32 v5, v5
	v_add_f32_e32 v4, 1.0, v4
	v_add_f32_e32 v5, 1.0, v5
	v_rcp_f32_e32 v4, v4
	v_rcp_f32_e32 v5, v5
	s_nop 0
	v_pk_mul_f32 v[0:1], v[0:1], v[4:5]
	v_lshlrev_b32_e32 v4, 16, v203
	v_and_b32_e32 v5, 0xffff0000, v203
	v_pk_fma_f32 v[2:3], v[98:99], v[4:5], v[2:3]
	v_cvt_pk_bf16_f32 v0, v0, v1
	v_mul_f32_e32 v4, 0x3d372713, v2
	v_mul_f32_e32 v5, 0x3d372713, v3
	v_mul_f32_e32 v4, v2, v4
	v_mul_f32_e32 v5, v3, v5
	v_fma_f32 v4, v2, v4, v2
	v_fma_f32 v5, v3, v5, v3
	v_mul_f32_e32 v4, 0xbfcc422a, v4
	v_mul_f32_e32 v5, 0xbfcc422a, v5
	v_mul_f32_e32 v4, 0x3fb8aa3b, v4
	v_mul_f32_e32 v5, 0x3fb8aa3b, v5
	v_exp_f32_e32 v4, v4
	v_exp_f32_e32 v5, v5
	v_add_f32_e32 v4, 1.0, v4
	v_add_f32_e32 v5, 1.0, v5
	v_rcp_f32_e32 v4, v4
	v_rcp_f32_e32 v5, v5
	s_nop 0
	v_pk_mul_f32 v[2:3], v[2:3], v[4:5]
	s_nop 0
	v_cvt_pk_bf16_f32 v1, v2, v3
	v_mad_i64_i32 v[2:3], s[6:7], v200, s35, v[148:149]
	global_store_dwordx2 v[2:3], v[0:1], off
	s_waitcnt lgkmcnt(0)
	s_mov_b64 s[6:7], 0
	s_cbranch_vccz .LBB0_185
	s_add_i32 s10, s10, 1
	s_cmp_eq_u32 s10, 4
	s_cbranch_scc0 .LBB0_184
	s_add_i32 s4, s4, 8
	s_add_i32 s8, s8, 8
	v_readlane_b32 s6, v255, 29
	s_mul_i32 s6, s6, 12
	s_sub_i32 s6, s4, s6
	s_cmp_gt_i32 s6, 11
	s_cbranch_scc0 .LBB0_179
